# layer 1: last 2288 tiles of its weight list converted by the idle workgroups of layer 1's q0 instead of layer 0's q6 slot
# baseline (speedup 1.0000x reference)
.LBB0_139:
	s_barrier
	v_readlane_b32 s4, v239, 37
	v_readlane_b32 s5, v241, 0
	v_readlane_b32 s6, v241, 9
	s_cmpk_lt_i32 s5, 0xcc
	s_cbranch_scc1 .LBB0_140
	s_cmpk_lg_i32 s6, 0x100
	s_cbranch_scc1 .LBB0_140
	s_add_i32 s56, s5, 0xffffff34
	s_cmp_lg_u32 s4, 0
	s_cbranch_scc1 .Ltrq0_l1
	s_mov_b32 s8, 0
	v_readlane_b32 s14, v239, 42
	v_readlane_b32 s15, v239, 43
	v_lshrrev_b32_e32 v117, 5, v178
	v_and_b32_e32 v168, 31, v178
	v_lshlrev_b32_e32 v116, 2, v168
	v_mul_u32_u24_e32 v16, 0x204, v117
	v_lshl_add_u32 v16, v116, 2, v16
	v_and_b32_e32 v168, 7, v178
	v_lshlrev_b32_e32 v120, 4, v168
	v_mul_u32_u24_e32 v17, 0x1020, v168
	v_lshrrev_b32_e32 v119, 3, v178
	v_lshl_add_u32 v17, v119, 2, v17
	s_add_i32 s4, s56, 4080
	s_mov_b32 s39, 0
	s_cmpk_lt_u32 s4, 0x6c0
	s_cbranch_scc0 .Ltrq0_t1_0
	s_lshr_b32 s5, s4, 5
	s_and_b32 s6, s4, 31
	v_readlane_b32 s28, v241, 11
	v_readlane_b32 s29, v241, 12
	s_mul_i32 s9, s8, 0x3430000
	s_movk_i32 s38, 0x6860
	s_mov_b32 s2, 0
	s_mul_i32 s3, s8, 0x1b00000
	s_movk_i32 s44, 0x1000
	s_mov_b32 s39, 1
	s_branch .Ltrq0_dec_0

.Ltrq0_l1:
	s_mov_b32 s8, 1
	v_readlane_b32 s14, v239, 42
	v_readlane_b32 s15, v239, 43
	v_lshrrev_b32_e32 v117, 5, v178
	v_and_b32_e32 v168, 31, v178
	v_lshlrev_b32_e32 v116, 2, v168
	v_mul_u32_u24_e32 v16, 0x204, v117
	v_lshl_add_u32 v16, v116, 2, v16
	v_and_b32_e32 v168, 7, v178
	v_lshlrev_b32_e32 v120, 4, v168
	v_mul_u32_u24_e32 v17, 0x1020, v168
	v_lshrrev_b32_e32 v119, 3, v178
	v_lshl_add_u32 v17, v119, 2, v17
	s_add_i32 s4, s56, 4080
	s_mov_b32 s39, 0
	s_cmpk_lt_u32 s4, 0x6c0
	s_cbranch_scc0 .Ltrq0b_t1_0
	s_lshr_b32 s5, s4, 5
	s_and_b32 s6, s4, 31
	v_readlane_b32 s28, v241, 11
	v_readlane_b32 s29, v241, 12
	s_mul_i32 s9, s8, 0x3430000
	s_movk_i32 s38, 0x6860
	s_mov_b32 s2, 0
	s_mul_i32 s3, s8, 0x1b00000
	s_movk_i32 s44, 0x1000
	s_mov_b32 s39, 1
	s_branch .Ltrq0b_dec_0

.Ltrq6_nosc:
	v_mov_b32_e32 v168, v16
	ds_write2_b32 v168, v100, v101 offset1:1
	ds_write2_b32 v168, v102, v103 offset0:2 offset1:3
	v_add_u32_e32 v168, 8256, v16
	ds_write2_b32 v168, v104, v105 offset1:1
	ds_write2_b32 v168, v106, v107 offset0:2 offset1:3
	v_add_u32_e32 v168, 16512, v16
	ds_write2_b32 v168, v108, v109 offset1:1
	ds_write2_b32 v168, v110, v111 offset0:2 offset1:3
	v_add_u32_e32 v168, 24768, v16
	ds_write2_b32 v168, v112, v113 offset1:1
	ds_write2_b32 v168, v114, v115 offset0:2 offset1:3
	s_add_i32 s56, s56, 244
	s_cmpk_lt_u32 s56, 0xff0
	s_cselect_b32 s7, 1, 0
	s_cbranch_scc0 .Ltrq6_nonext
	s_add_i32 s4, s56, 0
	s_mov_b32 s39, 0
	s_cmpk_lt_u32 s4, 0x6c0
	s_cbranch_scc0 .Ltrq6_t1_1
	s_lshr_b32 s5, s4, 5
	s_and_b32 s6, s4, 31
	v_readlane_b32 s28, v241, 11
	v_readlane_b32 s29, v241, 12
	s_mul_i32 s9, s8, 0x3430000
	s_movk_i32 s38, 0x6860
	s_mov_b32 s2, 0
	s_mul_i32 s3, s8, 0x1b00000
	s_movk_i32 s44, 0x1000
	s_mov_b32 s39, 1
	s_branch .Ltrq6_dec_1
